# first tickets of the ssm2/conv/gmlp/cvt dealt loops fetched together right after the attention loop (4 atomics in flight across the ssm1-done wait) instead of one exposed atomic round trip per loop en
# baseline (speedup 1.0000x reference)
; DI void wait_done(const Frame& F, gu32* ctr, unsigned need) {
;     if (F.tid == 0) { unsigned sp = 0; while (__hip_atomic_load(ctr, RLX_AGENT) < need) { __builtin_amdgcn_s_sleep(2); if (++sp > (1u << 22)) break; }
;         __builtin_amdgcn_fence(__ATOMIC_ACQUIRE, "agent"); asm volatile("s_waitcnt vmcnt(0)" ::: "memory"); }
; __global__ void __launch_bounds__(NTHR, 2) fwd(Args args) {
;     ...
;             wait_done(F, cnt_word(F, l, CNT_SSM1DONE), (unsigned)F.G);
.LBB0_1420:
	s_lshl_b64 s[0:1], s[4:5], 2
	v_readlane_b32 s2, v252, 3
	s_add_u32 s6, s2, s0
	v_readlane_b32 s0, v252, 4
	s_addc_u32 s7, s0, s1
	v_cmp_eq_u32_e32 vcc, 0, v0
	s_waitcnt vmcnt(0)
	s_barrier
	s_and_saveexec_b64 s[0:1], vcc
	s_xor_b64 s[0:1], exec, s[0:1]
	s_cbranch_execz .LBB0_1430
	global_atomic_add v229, v2, v197, s[6:7] offset:768 sc0
	global_atomic_add v230, v2, v197, s[6:7] sc0
	global_atomic_add v231, v2, v197, s[6:7] offset:256 sc0
	global_atomic_add v232, v2, v197, s[6:7] offset:2816 sc0
	s_mov_b32 s4, 0x400001
	s_branch .LBB0_1423

; #define DEAL_LOOP_DYN(F, ctr, N, BODY) do { gu32* _c = (ctr); int u = next_unit(F, _c); while (u < (N)) { const unsigned _t = deal_prefetch(F, _c); BODY; u = deal_publish(F, _t); } __syncthreads(); } while (0)
; DI int next_unit(const Frame& F, gu32* ctr) {
;     __syncthreads();
;     if (F.tid == 0) F.MISC[4] = __hip_atomic_fetch_add(ctr, 1u, RLX_AGENT);
;     __syncthreads();
;     return __builtin_amdgcn_readfirstlane((int)F.MISC[4]);
; }
; __global__ void __launch_bounds__(NTHR, 2) fwd(Args args) {
;     ...
;                 if (PH_ON(9)) DEAL_LOOP_DYN(F, cnt_word(F, l, CNT_SSM2 + 5 * rep), 288, ssm_pass2_unit(args, F, l, u));
.LBB0_1430:
	s_or_b64 exec, exec, s[0:1]
	v_writelane_b32 v249, s6, 33
	s_barrier
	s_nop 0
	v_writelane_b32 v249, s7, 34
	v_cmp_eq_u32_e64 s[24:25], 0, v0
	s_barrier
	s_and_saveexec_b64 s[0:1], s[24:25]
	s_cbranch_execz .LBB0_1434
	s_mov_b64 s[4:5], exec
	v_mbcnt_lo_u32_b32 v3, s4, 0
	v_mbcnt_hi_u32_b32 v3, s5, v3
	v_cmp_eq_u32_e32 vcc, 0, v3
	s_and_saveexec_b64 s[2:3], vcc
	s_cbranch_execz .LBB0_1433
	s_bcnt1_i32_b64 s4, s[4:5]
	v_mov_b32_e32 v4, s4
	v_readlane_b32 s4, v249, 33
	v_readlane_b32 s5, v249, 34
	s_nop 4
	v_mov_b32_e32 v4, v229

; #define DEAL_LOOP_DYN(F, ctr, N, BODY) do { gu32* _c = (ctr); int u = next_unit(F, _c); while (u < (N)) { const unsigned _t = deal_prefetch(F, _c); BODY; u = deal_publish(F, _t); } __syncthreads(); } while (0)
; DI int next_unit(const Frame& F, gu32* ctr) {
;     __syncthreads();
;     if (F.tid == 0) F.MISC[4] = __hip_atomic_fetch_add(ctr, 1u, RLX_AGENT);
;     __syncthreads();
;     return __builtin_amdgcn_readfirstlane((int)F.MISC[4]);
; }
; __global__ void __launch_bounds__(NTHR, 2) fwd(Args args) {
;     ...
;                 if (PH_ON(6)) DEAL_LOOP_DYN(F, cnt_word(F, l, CNT_CONV + 5 * rep), 288, conv_unit(args, F, l, u));
.LBB0_1488:
	s_barrier
	s_nop 0
	v_cmp_eq_u32_e64 s[36:37], 0, v0
	s_barrier
	s_and_saveexec_b64 s[0:1], s[36:37]
	s_cbranch_execz .LBB0_1492
	s_mov_b64 s[4:5], exec
	v_mbcnt_lo_u32_b32 v3, s4, 0
	v_mbcnt_hi_u32_b32 v3, s5, v3
	v_cmp_eq_u32_e32 vcc, 0, v3
	s_and_saveexec_b64 s[2:3], vcc
	s_cbranch_execz .LBB0_1491
	s_bcnt1_i32_b64 s4, s[4:5]
	v_mov_b32_e32 v4, s4
	v_readlane_b32 s4, v249, 33
	v_readlane_b32 s5, v249, 34
	s_nop 4
	v_mov_b32_e32 v4, v230

; #define DEAL_LOOP_DYN(F, ctr, N, BODY) do { gu32* _c = (ctr); int u = next_unit(F, _c); while (u < (N)) { const unsigned _t = deal_prefetch(F, _c); BODY; u = deal_publish(F, _t); } __syncthreads(); } while (0)
; DI int next_unit(const Frame& F, gu32* ctr) {
;     __syncthreads();
;     if (F.tid == 0) F.MISC[4] = __hip_atomic_fetch_add(ctr, 1u, RLX_AGENT);
;     __syncthreads();
;     return __builtin_amdgcn_readfirstlane((int)F.MISC[4]);
; }
; __global__ void __launch_bounds__(NTHR, 2) fwd(Args args) {
;     ...
;                 if (PH_ON(7)) DEAL_LOOP_DYN(F, cnt_word(F, l, CNT_GMLP + 5 * rep), 160, gmlp_unit(args, F, l, u));
.LBB0_1525:
	s_barrier
	s_nop 0
	v_cmp_eq_u32_e64 s[36:37], 0, v0
	s_barrier
	s_and_saveexec_b64 s[0:1], s[36:37]
	s_cbranch_execz .LBB0_1529
	s_mov_b64 s[4:5], exec
	v_mbcnt_lo_u32_b32 v3, s4, 0
	v_mbcnt_hi_u32_b32 v3, s5, v3
	v_cmp_eq_u32_e32 vcc, 0, v3
	s_and_saveexec_b64 s[2:3], vcc
	s_cbranch_execz .LBB0_1528
	s_bcnt1_i32_b64 s4, s[4:5]
	v_mov_b32_e32 v4, s4
	v_readlane_b32 s4, v249, 33
	v_readlane_b32 s5, v249, 34
	s_nop 4
	v_mov_b32_e32 v4, v231

; #define DEAL_LOOP_DYN(F, ctr, N, BODY) do { gu32* _c = (ctr); int u = next_unit(F, _c); while (u < (N)) { const unsigned _t = deal_prefetch(F, _c); BODY; u = deal_publish(F, _t); } __syncthreads(); } while (0)
; DI int next_unit(const Frame& F, gu32* ctr) {
;     __syncthreads();
;     if (F.tid == 0) F.MISC[4] = __hip_atomic_fetch_add(ctr, 1u, RLX_AGENT);
;     __syncthreads();
;     return __builtin_amdgcn_readfirstlane((int)F.MISC[4]);
; }
; __global__ void __launch_bounds__(NTHR, 2) fwd(Args args) {
;     ...
;               DEAL_LOOP_DYN(F, cnt_word(F, l, CNT_CVT), cvn, cvt_unit(args, F, cv0 + u * CV_PER)); }
.LBB0_1568:
	s_barrier
	s_nop 0
	v_cmp_eq_u32_e64 s[8:9], 0, v0
	s_barrier
	s_and_saveexec_b64 s[0:1], s[8:9]
	v_writelane_b32 v249, s69, 53
	v_writelane_b32 v249, s78, 54
	s_xor_b64 s[0:1], exec, s[0:1]
	s_mov_b32 s33, 0x400000
	v_writelane_b32 v249, s79, 55
	v_writelane_b32 v249, s96, 56
	s_nop 1
	v_writelane_b32 v249, s97, 57
	v_writelane_b32 v249, s8, 45
	s_nop 1
	v_writelane_b32 v249, s9, 46
	s_cbranch_execz .LBB0_1572
	s_mov_b64 s[4:5], exec
	v_mbcnt_lo_u32_b32 v3, s4, 0
	v_mbcnt_hi_u32_b32 v3, s5, v3
	v_cmp_eq_u32_e32 vcc, 0, v3
	s_and_saveexec_b64 s[2:3], vcc
	s_cbranch_execz .LBB0_1571
	s_bcnt1_i32_b64 s4, s[4:5]
	v_mov_b32_e32 v4, s4
	v_readlane_b32 s4, v249, 33
	v_readlane_b32 s5, v249, 34
	s_nop 4
	v_mov_b32_e32 v4, v232
